# no s_sleep stagger; tile slot bits 2<->5 swapped so co-resident blocks share A rows
# speedup vs baseline: 1.1176x; 1.0181x over previous
.LBB0_250:
	s_cmp_lt_i32 s84, 0
	s_cbranch_scc1 .LBB0_348
	s_bitcmp0_b32 s84, 8
	s_cbranch_scc1 .LBB0_253
	s_nop 0
.LBB0_253:
	s_and_b32 s2, s92, 7
	s_mov_b32 s20, 0
	s_mov_b32 s21, 1
	s_cmp_lg_u32 s2, 0
	s_mov_b32 s22, s92
	s_mov_b32 s23, s84
	s_cbranch_scc1 .LBB0_255
	s_and_b32 s20, s84, 7
	s_lshr_b32 s23, s84, 3
	s_lshr_b32 s22, s23, 2
	s_lshr_b32 vcc_lo, s23, 5
	s_xor_b32 s22, s22, vcc_lo
	s_and_b32 s22, s22, 1
	s_mul_i32 s22, s22, 36
	s_xor_b32 s23, s23, s22
	s_ashr_i32 s22, s92, 3
	s_mov_b32 s21, 8

.LBB0_403:
	s_add_u32 s26, s88, 0x1840000
	s_addc_u32 s27, s89, 0
	s_add_u32 s28, s88, 0x4c00000
	s_addc_u32 s29, s89, 0
	s_add_u32 s30, s88, 0x244000
	s_addc_u32 s31, s89, 0
	s_cmpk_lt_i32 s84, 0x80
	s_cselect_b64 s[2:3], -1, 0
	s_cmpk_gt_i32 s84, 0x7f
	s_cselect_b64 s[0:1], -1, 0
	s_add_i32 s14, s92, 0xffffff80
	v_lshlrev_b32_e32 v0, 3, v196
	s_cmpk_lt_u32 s84, 0x80
	v_lshrrev_b32_e32 v199, 6, v196
	v_lshrrev_b32_e32 v200, 3, v196
	v_and_b32_e32 v198, 56, v0
	v_and_b32_e32 v197, 15, v196
	s_cbranch_scc1 .LBB0_521
	s_andn2_b64 vcc, exec, s[0:1]
	s_cbranch_vccnz .LBB0_503
	s_bitcmp0_b32 s84, 8
	s_mov_b32 s15, 0
	s_cbranch_scc1 .LBB0_407
	s_nop 0

.LBB0_812:
	v_mov_b32_e32 v252, 0
	ds_read_b64 v[250:251], v252
	s_waitcnt lgkmcnt(0)
	v_lshlrev_b32_e32 v0, 3, v196
	s_cmp_lt_i32 s84, 0
	v_lshrrev_b32_e32 v148, 3, v196
	v_and_b32_e32 v149, 56, v0
	s_cbranch_scc1 .LBB0_822
	s_bitcmp0_b32 s84, 8
	s_cbranch_scc1 .LBB0_815
	s_nop 0
.LBB0_815:
	s_and_b32 s2, s92, 7
	s_mov_b32 s10, 0
	s_mov_b32 s11, 1
	s_cmp_lg_u32 s2, 0
	s_mov_b32 s12, s92
	s_mov_b32 s13, s84
	s_cbranch_scc1 .LBB0_817
	s_and_b32 s10, s84, 7
	s_lshr_b32 s13, s84, 3
	s_lshr_b32 s12, s13, 2
	s_lshr_b32 vcc_lo, s13, 5
	s_xor_b32 s12, s12, vcc_lo
	s_and_b32 s12, s12, 1
	s_mul_i32 s12, s12, 36
	s_xor_b32 s13, s13, s12
	s_ashr_i32 s12, s92, 3
	s_mov_b32 s11, 8

.LBB0_963:
	v_mov_b32_e32 v252, 0
	ds_read_b64 v[250:251], v252
	s_waitcnt lgkmcnt(0)
	s_cmp_lt_i32 s84, 0
	s_cbranch_scc1 .LBB0_979
	s_bitcmp0_b32 s84, 8
	s_cbranch_scc1 .LBB0_966
	s_nop 0

.LBB0_1114:
	s_and_b32 s2, s92, 7
	s_mov_b32 s8, 0
	s_mov_b32 s9, 1
	s_cmp_lg_u32 s2, 0
	s_mov_b32 s10, s92
	s_mov_b32 s11, s84
	s_cbranch_scc1 .LBB0_1116
	s_and_b32 s8, s84, 7
	s_lshr_b32 s11, s84, 3
	s_lshr_b32 s10, s11, 2
	s_lshr_b32 vcc_lo, s11, 5
	s_xor_b32 s10, s10, vcc_lo
	s_and_b32 s10, s10, 1
	s_mul_i32 s10, s10, 36
	s_xor_b32 s11, s11, s10
	s_ashr_i32 s10, s92, 3
	s_mov_b32 s9, 8

.LBB0_1238:
	s_and_b32 s0, s92, 7
	s_mov_b32 s26, 0
	s_mov_b32 s27, 1
	s_cmp_lg_u32 s0, 0
	s_mov_b32 s28, s92
	s_mov_b32 s29, s84
	s_cbranch_scc1 .LBB0_1240
	s_and_b32 s26, s84, 7
	s_lshr_b32 s29, s84, 3
	s_lshr_b32 s28, s29, 2
	s_lshr_b32 vcc_lo, s29, 5
	s_xor_b32 s28, s28, vcc_lo
	s_and_b32 s28, s28, 1
	s_mul_i32 s28, s28, 36
	s_xor_b32 s29, s29, s28
	s_ashr_i32 s28, s92, 3
	s_mov_b32 s27, 8
